# natten and GQA tile loops: the next tile's global loads are issued after the current tile's LDS reads instead of ahead of them (address temporaries moved to unused VGPRs)
# baseline (speedup 1.0000x reference)
; #define LAS __attribute__((address_space(3)))
; __device__ __forceinline__ int crow(int r, int hi) { return (r & 3) + 8 * (r >> 2) + 4 * hi; }
; #define ISSUE(t) do { int tok_ = TILE_TOK0(t) + lrow; tok_ = tok_ > LT - 1 ? LT - 1 : tok_; const bf16_t* src_ = pb + (size_t)tok_ * INC; \
;         _Pragma("unroll") for (int s = 0; s < NS; ++s) pre[s] = *(const u32x4*)(src_ + STREAM_COL(s)); } while (0)
; template <int MODE> __device__ __forceinline__ void attn_unit(const AttnP& P, int u, LAS char* lds, bool fill) {
;     ...
;     for (int t = 0; t < nt; ++t) {
;         __syncthreads();
; #pragma unroll
;         for (int s = 0; s < NS; ++s) *(LAS u32x4*)(lds + s * ASLOT + lrow * APITCH + lch * 16) = pre[s];
;         __syncthreads();
;         if (t + 1 < nt) ISSUE(t + 1);
;         const int tok0 = TILE_TOK0(t);
;         f32x16 p0, p1;
; #pragma unroll
;         for (int r = 0; r < 16; ++r) { p0[r] = 0.f; p1[r] = 0.f; }
; #pragma unroll
;         for (int ds = 0; ds < 4; ++ds) {
;             const bf16x8 k0 = *(const LAS bf16x8*)(kb + ds * 32);
;             const bf16x8 k1 = *(const LAS bf16x8*)(kb + 32 * APITCH + ds * 32);
;             p0 = __builtin_amdgcn_mfma_f32_32x32x16_bf16(k0, qr[ds], p0, 0, 0, 0);
;             p1 = __builtin_amdgcn_mfma_f32_32x32x16_bf16(k1, qr[ds], p1, 0, 0, 0);
;         }
;         if (MODE == 0) {
;             const bool farl = (tok0 + 63 + 128 <= qtok0), farr = (tok0 - (qtok0 + 31) >= 128) && (tok0 + 64 <= LT);
;             if (farl || farr) { const float cb = farl ? mytab[0] : mytab[256];
; #pragma unroll
;                 for (int r = 0; r < 16; ++r) { p0[r] += cb; p1[r] += cb; } }
;             else {
; #pragma unroll
;                 for (int r = 0; r < 16; ++r) { const int tk0 = tok0 + crow(r, hi), tk1 = tk0 + 32;
;                     int i0 = tk0 - tq + 128; i0 = i0 < 0 ? 0 : (i0 > 256 ? 256 : i0); int i1 = tk1 - tq + 128; i1 = i1 < 0 ? 0 : (i1 > 256 ? 256 : i1);
;                     p0[r] = tk0 < LT ? p0[r] + mytab[i0] : NEGV; p1[r] = tk1 < LT ? p1[r] + mytab[i1] : NEGV; } }
;         } else if (MODE == 2) {
;           if (tok0 >= NMETA && tok0 + 64 <= LT) {
;             const LAS float* t2 = mytab2 + (tok0 - tq + 191 + 4 * hi);
; #pragma unroll
;             for (int r = 0; r < 16; ++r) { p0[r] += t2[(r & 3) + 8 * (r >> 2)]; p1[r] += t2[(r & 3) + 8 * (r >> 2) + 32]; }
.LBB0_1079:
	s_add_i32 s38, s38, 1
	s_waitcnt lgkmcnt(0)
	s_barrier
	s_waitcnt vmcnt(1)
	ds_write_b128 v0, v[118:121]
	s_waitcnt vmcnt(0)
	ds_write_b128 v0, v[114:117] offset:9216
	s_waitcnt lgkmcnt(0)
	s_barrier
	s_add_i32 s15, s35, s34
	s_add_i32 s16, s15, 48
	s_cmpk_lt_u32 s16, 0xfc1
	s_cbranch_scc0 .Lgqa1_slowpre
	ds_read_b128 v[66:69], v127
	ds_read_b128 v[70:73], v127 offset:4608
	ds_read_b128 v[74:77], v127 offset:32
	ds_read_b128 v[78:81], v127 offset:4640
	ds_read_b128 v[82:85], v127 offset:64
	ds_read_b128 v[86:89], v127 offset:4672
	ds_read_b128 v[90:93], v127 offset:96
	ds_read_b128 v[94:97], v127 offset:4704
	ds_read2_b32 v[34:35], v131 offset0:0 offset1:1
	ds_read2_b32 v[36:37], v131 offset0:2 offset1:3
	ds_read2_b32 v[38:39], v131 offset0:8 offset1:9
	ds_read2_b32 v[40:41], v131 offset0:10 offset1:11
	ds_read2_b32 v[42:43], v131 offset0:16 offset1:17
	ds_read2_b32 v[44:45], v131 offset0:18 offset1:19
	ds_read2_b32 v[46:47], v131 offset0:24 offset1:25
	ds_read2_b32 v[48:49], v131 offset0:26 offset1:27
	ds_read2_b32 v[50:51], v131 offset0:32 offset1:33
	ds_read2_b32 v[52:53], v131 offset0:34 offset1:35
	ds_read2_b32 v[54:55], v131 offset0:40 offset1:41
	ds_read2_b32 v[56:57], v131 offset0:42 offset1:43
	ds_read2_b32 v[58:59], v131 offset0:48 offset1:49
	ds_read2_b32 v[60:61], v131 offset0:50 offset1:51
	ds_read2_b32 v[62:63], v131 offset0:56 offset1:57
	ds_read2_b32 v[64:65], v131 offset0:58 offset1:59
	s_cmp_ge_i32 s38, s30
	s_cbranch_scc1 .Lgqa1_noload
	s_add_i32 s15, s34, 0x80
	s_add_i32 s16, s14, s34
	s_and_b64 s[0:1], s[46:47], exec
	s_cselect_b32 s0, s16, s15
	v_add_u32_e32 v206, s0, v126
	v_min_i32_e32 v206, 0x100f, v206
	v_mad_i64_i32 v[206:207], s[0:1], v206, s51, v[122:123]
	v_lshl_add_u64 v[208:209], v[206:207], 0, s[80:81]
	s_mov_b32 s59, s81
	v_lshl_add_u64 v[206:207], v[206:207], 0, s[58:59]
	global_load_dwordx4 v[118:121], v[208:209], off
	global_load_dwordx4 v[114:117], v[206:207], off
.Lgqa1_noload:
	s_waitcnt lgkmcnt(8)
	v_mfma_f32_32x32x16_bf16 v[34:49], v[66:69], v[98:101], v[34:49]
	s_waitcnt lgkmcnt(0)
	v_mfma_f32_32x32x16_bf16 v[50:65], v[70:73], v[98:101], v[50:65]
	v_mfma_f32_32x32x16_bf16 v[34:49], v[74:77], v[102:105], v[34:49]
	v_mfma_f32_32x32x16_bf16 v[50:65], v[78:81], v[102:105], v[50:65]
	v_mfma_f32_32x32x16_bf16 v[34:49], v[82:85], v[106:109], v[34:49]
	v_mfma_f32_32x32x16_bf16 v[50:65], v[86:89], v[106:109], v[50:65]
	v_mfma_f32_32x32x16_bf16 v[34:49], v[90:93], v[110:113], v[34:49]
	v_mfma_f32_32x32x16_bf16 v[50:65], v[94:97], v[110:113], v[50:65]
	s_branch .Lgqa1_tail
.Lgqa1_slowpre:
	s_cmp_ge_i32 s38, s30
	s_cbranch_scc1 .Lgqa1_noload_s
	s_add_i32 s15, s34, 0x80
	s_add_i32 s16, s14, s34
	s_and_b64 s[0:1], s[46:47], exec
	s_cselect_b32 s0, s16, s15
	v_add_u32_e32 v34, s0, v126
	v_min_i32_e32 v34, 0x100f, v34
	v_mad_i64_i32 v[34:35], s[0:1], v34, s51, v[122:123]
	v_lshl_add_u64 v[36:37], v[34:35], 0, s[80:81]
	s_mov_b32 s59, s81
	v_lshl_add_u64 v[34:35], v[34:35], 0, s[58:59]
	global_load_dwordx4 v[118:121], v[36:37], off
	global_load_dwordx4 v[114:117], v[34:35], off
.Lgqa1_noload_s:
	s_add_i32 s15, s35, s34
	s_add_i32 s16, s15, 48
.Lgqa1_slow:
	ds_read_b128 v[34:37], v127 offset:4608
	ds_read_b128 v[38:41], v127
	ds_read_b128 v[42:45], v127 offset:32
	s_add_i32 s15, s35, s34
	s_add_i32 s16, s15, 48
	s_waitcnt lgkmcnt(2)
	v_mfma_f32_32x32x16_bf16 v[66:81], v[34:37], v[98:101], 0
	ds_read_b128 v[34:37], v127 offset:4640
	s_mov_b64 s[0:1], -1
	s_cmpk_lt_u32 s16, 0xfc1
	s_waitcnt lgkmcnt(2)
	v_mfma_f32_32x32x16_bf16 v[82:97], v[38:41], v[98:101], 0
	s_waitcnt lgkmcnt(1)
	v_mfma_f32_32x32x16_bf16 v[82:97], v[42:45], v[102:105], v[82:97]
	s_waitcnt lgkmcnt(0)
	v_mfma_f32_32x32x16_bf16 v[66:81], v[34:37], v[102:105], v[66:81]
	ds_read_b128 v[34:37], v127 offset:64
	ds_read_b128 v[38:41], v127 offset:4672
	s_waitcnt lgkmcnt(1)
	v_mfma_f32_32x32x16_bf16 v[82:97], v[34:37], v[106:109], v[82:97]
	s_waitcnt lgkmcnt(0)
	v_mfma_f32_32x32x16_bf16 v[66:81], v[38:41], v[106:109], v[66:81]
	ds_read_b128 v[34:37], v127 offset:96
	ds_read_b128 v[38:41], v127 offset:4704
	s_waitcnt lgkmcnt(1)
	v_mfma_f32_32x32x16_bf16 v[82:97], v[34:37], v[110:113], v[82:97]
	s_waitcnt lgkmcnt(0)
	v_mfma_f32_32x32x16_bf16 v[66:81], v[38:41], v[110:113], v[66:81]
	v_add_u32_e32 v49, s34, v132
	v_add_u32_e32 v134, s34, v133
	v_add_u32_e32 v35, 64, v49
	v_add_u32_e32 v34, 0xc0, v134
	v_cmp_gt_i32_e32 vcc, 16, v35
	v_cmp_gt_u32_e64 s[44:45], s6, v34
	s_or_b64 s[0:1], vcc, s[44:45]
	v_cmp_gt_i32_e32 vcc, s37, v35
	s_and_b64 s[28:29], vcc, s[0:1]
	v_mov_b32_e32 v50, 0xf149f2ca
	v_mov_b32_e32 v34, 0xf149f2ca
	s_and_saveexec_b64 s[0:1], s[28:29]
	s_cbranch_execz .LBB0_1084
	v_add_u32_e32 v34, 64, v134
	v_med3_i32 v34, v34, s87, v240
	v_lshl_add_u32 v34, v34, 2, s31
	ds_read_b32 v34, v34 offset:512
	s_waitcnt lgkmcnt(0)
	v_add_f32_e32 v34, v82, v34

; #define LAS __attribute__((address_space(3)))
; template <int MODE> __device__ __forceinline__ void attn_unit(const AttnP& P, int u, LAS char* lds, bool fill) {
;     ...
;     for (int t = 0; t < nt; ++t) {
;         __syncthreads();
; #pragma unroll
;         for (int s = 0; s < NS; ++s) *(LAS u32x4*)(lds + s * ASLOT + lrow * APITCH + lch * 16) = pre[s];
;         __syncthreads();
;         if (t + 1 < nt) ISSUE(t + 1);
;         const int tok0 = TILE_TOK0(t);
;         f32x16 p0, p1;
; #pragma unroll
;         for (int r = 0; r < 16; ++r) { p0[r] = 0.f; p1[r] = 0.f; }
; #pragma unroll
;         for (int ds = 0; ds < 4; ++ds) {
;             const bf16x8 k0 = *(const LAS bf16x8*)(kb + ds * 32);
;             const bf16x8 k1 = *(const LAS bf16x8*)(kb + 32 * APITCH + ds * 32);
;             p0 = __builtin_amdgcn_mfma_f32_32x32x16_bf16(k0, qr[ds], p0, 0, 0, 0);
;             p1 = __builtin_amdgcn_mfma_f32_32x32x16_bf16(k1, qr[ds], p1, 0, 0, 0);
;         }
;         if (MODE == 0) {
;             const bool farl = (tok0 + 63 + 128 <= qtok0), farr = (tok0 - (qtok0 + 31) >= 128) && (tok0 + 64 <= LT);
;             if (farl || farr) { const float cb = farl ? mytab[0] : mytab[256];
; #pragma unroll
;                 for (int r = 0; r < 16; ++r) { p0[r] += cb; p1[r] += cb; } }
;             else {
; #pragma unroll
;                 for (int r = 0; r < 16; ++r) { const int tk0 = tok0 + crow(r, hi), tk1 = tk0 + 32;
;                     int i0 = tk0 - tq + 128; i0 = i0 < 0 ? 0 : (i0 > 256 ? 256 : i0); int i1 = tk1 - tq + 128; i1 = i1 < 0 ? 0 : (i1 > 256 ? 256 : i1);
;                     p0[r] = tk0 < LT ? p0[r] + mytab[i0] : NEGV; p1[r] = tk1 < LT ? p1[r] + mytab[i1] : NEGV; } }
;         } else if (MODE == 2) {
;           if (tok0 >= NMETA && tok0 + 64 <= LT) {
;             const LAS float* t2 = mytab2 + (tok0 - tq + 191 + 4 * hi);
; #pragma unroll
;             for (int r = 0; r < 16; ++r) { p0[r] += t2[(r & 3) + 8 * (r >> 2)]; p1[r] += t2[(r & 3) + 8 * (r >> 2) + 32]; }
;           } else
; #pragma unroll
;             for (int r = 0; r < 16; ++r) { const int tk0 = tok0 + crow(r, hi), tk1 = tk0 + 32; const int r0 = tk0 - tq, r1 = tk1 - tq;
;                 int i0 = r0 + 128; i0 = i0 < 0 ? 0 : (i0 > 256 ? 256 : i0); int i1 = r1 + 128; i1 = i1 < 0 ? 0 : (i1 > 256 ? 256 : i1);
.Lnat1L_loop:
	s_waitcnt lgkmcnt(0)
	s_barrier
	s_waitcnt vmcnt(7)
	ds_write_b128 v165, v[82:85]
	s_waitcnt vmcnt(6)
	ds_write_b128 v165, v[86:89] offset:9216
	s_waitcnt vmcnt(5)
	ds_write_b128 v165, v[90:93] offset:18432
	s_waitcnt vmcnt(4)
	ds_write_b128 v165, v[94:97] offset:27648
	s_waitcnt vmcnt(3)
	ds_write_b128 v165, v[98:101] offset:36864
	s_waitcnt vmcnt(2)
	ds_write_b128 v165, v[102:105] offset:46080
	s_waitcnt vmcnt(1)
	ds_write_b128 v165, v[106:109] offset:55296
	s_waitcnt vmcnt(0)
	ds_write_b128 v165, v[110:113] offset:64512
	s_waitcnt lgkmcnt(0)
	s_barrier
	v_mov_b32_e32 v117, s17
	v_cndmask_b32_e64 v117, v117, v116, s[44:45]
	v_lshl_add_u32 v184, v132, 2, v117
	ds_read_b128 v[118:121], v0
	ds_read_b128 v[128:131], v0 offset:4608
	ds_read_b128 v[168:171], v0 offset:32
	ds_read_b128 v[172:175], v0 offset:4640
	ds_read_b128 v[176:179], v0 offset:64
	ds_read_b128 v[180:183], v0 offset:4672
	ds_read2_b32 v[50:51], v184 offset0:0 offset1:1
	ds_read2_b32 v[52:53], v184 offset0:2 offset1:3
	ds_read2_b32 v[54:55], v184 offset0:8 offset1:9
	ds_read2_b32 v[56:57], v184 offset0:10 offset1:11
	ds_read2_b32 v[58:59], v184 offset0:16 offset1:17
	ds_read2_b32 v[60:61], v184 offset0:18 offset1:19
	ds_read2_b32 v[62:63], v184 offset0:24 offset1:25
	ds_read2_b32 v[64:65], v184 offset0:26 offset1:27
	ds_read2_b32 v[34:35], v184 offset0:32 offset1:33
	ds_read2_b32 v[36:37], v184 offset0:34 offset1:35
	s_cmpk_eq_i32 s12, 0x1c0
	s_cbranch_scc1 .Lnat1L_noload
	v_add_u32_e32 v206, s12, v115
	v_min_i32_e32 v206, 0x100f, v206
	v_mad_i64_i32 v[206:207], s[14:15], v206, s51, v[126:127]
	v_lshl_add_u64 v[208:209], v[206:207], 0, s[80:81]
	s_mov_b32 s1, s81
	s_mov_b32 s39, s81
	v_lshl_add_u64 v[210:211], v[206:207], 0, s[0:1]
	global_load_dwordx4 v[82:85], v[208:209], off
	global_load_dwordx4 v[86:89], v[210:211], off
	v_lshl_add_u64 v[208:209], v[206:207], 0, s[38:39]
	s_mov_b32 s43, s81
	s_mov_b32 s47, s81
	v_lshl_add_u64 v[210:211], v[206:207], 0, s[42:43]
	global_load_dwordx4 v[90:93], v[208:209], off
	global_load_dwordx4 v[94:97], v[210:211], off
	v_lshl_add_u64 v[208:209], v[206:207], 0, s[46:47]
	s_mov_b32 s49, s81
	s_mov_b32 s59, s81
	v_lshl_add_u64 v[210:211], v[206:207], 0, s[48:49]
	global_load_dwordx4 v[98:101], v[208:209], off
	global_load_dwordx4 v[102:105], v[210:211], off
	v_lshl_add_u64 v[208:209], v[206:207], 0, s[58:59]
	s_mov_b32 s61, s81
	v_lshl_add_u64 v[206:207], v[206:207], 0, s[60:61]
	global_load_dwordx4 v[106:109], v[208:209], off
	global_load_dwordx4 v[110:113], v[206:207], off
; template <int MODE> __device__ __forceinline__ void attn_unit(const AttnP& P, int u, LAS char* lds, bool fill) {
;     ...
;         for (int ds = 0; ds < 4; ++ds) {
;             const bf16x8 k0 = *(const LAS bf16x8*)(kb + ds * 32);
;             const bf16x8 k1 = *(const LAS bf16x8*)(kb + 32 * APITCH + ds * 32);
;             p0 = __builtin_amdgcn_mfma_f32_32x32x16_bf16(k0, qr[ds], p0, 0, 0, 0);
;             p1 = __builtin_amdgcn_mfma_f32_32x32x16_bf16(k1, qr[ds], p1, 0, 0, 0);
;         }
;         if (MODE == 0) {
;             const bool farl = (tok0 + 63 + 128 <= qtok0), farr = (tok0 - (qtok0 + 31) >= 128) && (tok0 + 64 <= LT);
;             if (farl || farr) { const float cb = farl ? mytab[0] : mytab[256];
; #pragma unroll
;                 for (int r = 0; r < 16; ++r) { p0[r] += cb; p1[r] += cb; } }
;             else {
; #pragma unroll
;                 for (int r = 0; r < 16; ++r) { const int tk0 = tok0 + crow(r, hi), tk1 = tk0 + 32;
;                     int i0 = tk0 - tq + 128; i0 = i0 < 0 ? 0 : (i0 > 256 ? 256 : i0); int i1 = tk1 - tq + 128; i1 = i1 < 0 ? 0 : (i1 > 256 ? 256 : i1);
;                     p0[r] = tk0 < LT ? p0[r] + mytab[i0] : NEGV; p1[r] = tk1 < LT ? p1[r] + mytab[i1] : NEGV; } }
;         } else if (MODE == 2) {
;           if (tok0 >= NMETA && tok0 + 64 <= LT) {
;             const LAS float* t2 = mytab2 + (tok0 - tq + 191 + 4 * hi);
; #pragma unroll
;             for (int r = 0; r < 16; ++r) { p0[r] += t2[(r & 3) + 8 * (r >> 2)]; p1[r] += t2[(r & 3) + 8 * (r >> 2) + 32]; }
;           } else
; #pragma unroll
;             for (int r = 0; r < 16; ++r) { const int tk0 = tok0 + crow(r, hi), tk1 = tk0 + 32; const int r0 = tk0 - tq, r1 = tk1 - tq;
;                 int i0 = r0 + 128; i0 = i0 < 0 ? 0 : (i0 > 256 ? 256 : i0); int i1 = r1 + 128; i1 = i1 < 0 ? 0 : (i1 > 256 ? 256 : i1);
;                 const bool v0 = (tk0 < NMETA || (r0 >= -128 && r0 <= 128)) && tk0 < LT, v1 = (tk1 < NMETA || (r1 >= -128 && r1 <= 128)) && tk1 < LT;
;                 p0[r] = v0 ? p0[r] + mytab[i0] : NEGV; p1[r] = v1 ? p1[r] + mytab[i1] : NEGV; }
;         } else {
;             if (t == 0) {
; #pragma unroll
;                 for (int r = 0; r < 16; ++r) { const int k0 = crow(r, hi); p0[r] = k0 < NMETA ? p0[r] : NEGV; p1[r] = NEGV; }
;             } else {
;                 const int roff = (rs_ + t - 1) - x2 + 7;
.Lnat1L_noload:
	s_waitcnt lgkmcnt(9)
	v_add_f32_e32 v50, v50, v133
	v_add_f32_e32 v51, v51, v135
	s_waitcnt lgkmcnt(8)
	v_add_f32_e32 v52, v52, v137
	v_add_f32_e32 v53, v53, v139
	s_waitcnt lgkmcnt(7)
	v_add_f32_e32 v54, v54, v141
	v_add_f32_e32 v55, v55, v143
	s_waitcnt lgkmcnt(6)
	v_add_f32_e32 v56, v56, v145
	v_add_f32_e32 v57, v57, v147
	s_waitcnt lgkmcnt(5)
	v_add_f32_e32 v58, v58, v149
	v_add_f32_e32 v59, v59, v151
	s_waitcnt lgkmcnt(4)
	v_add_f32_e32 v60, v60, v153
	v_add_f32_e32 v61, v61, v155
	s_waitcnt lgkmcnt(3)
	v_add_f32_e32 v62, v62, v157
	v_add_f32_e32 v63, v63, v159
	s_waitcnt lgkmcnt(2)
	v_add_f32_e32 v64, v64, v161
	v_add_f32_e32 v65, v65, v163
	s_waitcnt lgkmcnt(1)
	v_add_f32_e32 v34, v34, v134
	v_add_f32_e32 v35, v35, v136
	s_waitcnt lgkmcnt(0)
	v_add_f32_e32 v36, v36, v138
	v_add_f32_e32 v37, v37, v140
	v_mfma_f32_32x32x16_bf16 v[50:65], v[118:121], v[66:69], v[50:65]
	ds_read_b128 v[118:121], v0 offset:96
	v_mfma_f32_32x32x16_bf16 v[34:49], v[128:131], v[66:69], v[34:49]
	ds_read_b128 v[128:131], v0 offset:4704
	v_mfma_f32_32x32x16_bf16 v[50:65], v[168:171], v[70:73], v[50:65]
	ds_read_b64_tr_b16 v[168:169], v166 offset:9216
	ds_read_b64_tr_b16 v[170:171], v166 offset:10368
	v_mfma_f32_32x32x16_bf16 v[34:49], v[172:175], v[70:73], v[34:49]
	ds_read_b64_tr_b16 v[172:173], v166 offset:9280
	ds_read_b64_tr_b16 v[174:175], v166 offset:10432
	v_mfma_f32_32x32x16_bf16 v[50:65], v[176:179], v[74:77], v[50:65]
	ds_read_b64_tr_b16 v[176:177], v166 offset:11520
	ds_read_b64_tr_b16 v[178:179], v166 offset:12672
	v_mfma_f32_32x32x16_bf16 v[34:49], v[180:183], v[74:77], v[34:49]
	ds_read_b64_tr_b16 v[180:181], v166 offset:11584
	ds_read_b64_tr_b16 v[182:183], v166 offset:12736
	s_waitcnt lgkmcnt(9)
	v_mfma_f32_32x32x16_bf16 v[50:65], v[118:121], v[78:81], v[50:65]
	s_waitcnt lgkmcnt(8)
	v_mfma_f32_32x32x16_bf16 v[34:49], v[128:131], v[78:81], v[34:49]
	ds_read_b64_tr_b16 v[118:119], v166 offset:13824
	ds_read_b64_tr_b16 v[120:121], v166 offset:14976
	ds_read_b64_tr_b16 v[128:129], v166 offset:13888
	ds_read_b64_tr_b16 v[130:131], v166 offset:15040
	s_nop 7
	v_max3_f32 v117, v50, v51, v52
	v_max3_f32 v184, v60, v61, v62
	v_max3_f32 v117, v117, v53, v54
	v_max3_f32 v184, v184, v63, v64
	v_max3_f32 v117, v117, v55, v56
	v_max3_f32 v184, v184, v65, v34
	v_max3_f32 v117, v117, v57, v58
	v_max3_f32 v184, v184, v35, v36
	v_max3_f32 v117, v117, v59, v37
	v_max_f32_e32 v117, v117, v184
	v_mov_b32_e32 v184, v117
	s_nop 1
	v_permlane32_swap_b32_e32 v117, v184
	v_max_f32_e32 v117, v117, v184
	v_cmp_lt_f32_e32 vcc, 0x41000000, v117
	s_cbranch_vccz .Lnat1L_noresc
	v_max_f32_e32 v117, 0, v117
	v_exp_f32_e64 v184, -v117
	v_add_f32_e32 v167, v167, v117
	v_sub_f32_e32 v133, v133, v117
	v_sub_f32_e32 v135, v135, v117
	v_sub_f32_e32 v137, v137, v117
	v_sub_f32_e32 v139, v139, v117
	v_sub_f32_e32 v141, v141, v117
	v_sub_f32_e32 v143, v143, v117
	v_sub_f32_e32 v145, v145, v117
	v_sub_f32_e32 v147, v147, v117
	v_sub_f32_e32 v149, v149, v117
	v_sub_f32_e32 v151, v151, v117
	v_sub_f32_e32 v153, v153, v117
	v_sub_f32_e32 v155, v155, v117
	v_sub_f32_e32 v157, v157, v117
	v_sub_f32_e32 v159, v159, v117
	v_sub_f32_e32 v161, v161, v117
	v_sub_f32_e32 v163, v163, v117
	v_sub_f32_e32 v134, v134, v117
	v_sub_f32_e32 v136, v136, v117
	v_sub_f32_e32 v138, v138, v117
	v_sub_f32_e32 v140, v140, v117
	v_sub_f32_e32 v50, v50, v117
	v_sub_f32_e32 v51, v51, v117
	v_sub_f32_e32 v52, v52, v117
	v_sub_f32_e32 v53, v53, v117
	v_sub_f32_e32 v54, v54, v117
	v_sub_f32_e32 v55, v55, v117
	v_sub_f32_e32 v56, v56, v117
	v_sub_f32_e32 v57, v57, v117
	v_sub_f32_e32 v58, v58, v117
	v_sub_f32_e32 v59, v59, v117
	v_sub_f32_e32 v60, v60, v117
	v_sub_f32_e32 v61, v61, v117
	v_sub_f32_e32 v62, v62, v117
	v_sub_f32_e32 v63, v63, v117
	v_sub_f32_e32 v64, v64, v117
	v_sub_f32_e32 v65, v65, v117
	v_sub_f32_e32 v34, v34, v117
	v_sub_f32_e32 v35, v35, v117
	v_sub_f32_e32 v36, v36, v117
	v_sub_f32_e32 v37, v37, v117
	v_mul_f32_e32 v2, v2, v184
	v_mul_f32_e32 v3, v3, v184
	v_mul_f32_e32 v4, v4, v184
	v_mul_f32_e32 v5, v5, v184
	v_mul_f32_e32 v6, v6, v184
	v_mul_f32_e32 v7, v7, v184
	v_mul_f32_e32 v8, v8, v184
	v_mul_f32_e32 v9, v9, v184
	v_mul_f32_e32 v10, v10, v184
	v_mul_f32_e32 v11, v11, v184
	v_mul_f32_e32 v12, v12, v184
	v_mul_f32_e32 v13, v13, v184
	v_mul_f32_e32 v14, v14, v184
	v_mul_f32_e32 v15, v15, v184
	v_mul_f32_e32 v16, v16, v184
	v_mul_f32_e32 v17, v17, v184
	v_mul_f32_e32 v18, v18, v184
	v_mul_f32_e32 v19, v19, v184
	v_mul_f32_e32 v20, v20, v184
	v_mul_f32_e32 v21, v21, v184
	v_mul_f32_e32 v22, v22, v184
	v_mul_f32_e32 v23, v23, v184
	v_mul_f32_e32 v24, v24, v184
	v_mul_f32_e32 v25, v25, v184
	v_mul_f32_e32 v26, v26, v184
	v_mul_f32_e32 v27, v27, v184
	v_mul_f32_e32 v28, v28, v184
	v_mul_f32_e32 v29, v29, v184
	v_mul_f32_e32 v30, v30, v184
	v_mul_f32_e32 v31, v31, v184
	v_mul_f32_e32 v32, v32, v184
	v_mul_f32_e32 v33, v33, v184
	v_mul_f32_e32 v114, v114, v184
	s_nop 1

; #define LAS __attribute__((address_space(3)))
; template <int MODE> __device__ __forceinline__ void attn_unit(const AttnP& P, int u, LAS char* lds, bool fill) {
;     ...
;     for (int t = 0; t < nt; ++t) {
;         __syncthreads();
; #pragma unroll
;         for (int s = 0; s < NS; ++s) *(LAS u32x4*)(lds + s * ASLOT + lrow * APITCH + lch * 16) = pre[s];
;         __syncthreads();
;         if (t + 1 < nt) ISSUE(t + 1);
;         const int tok0 = TILE_TOK0(t);
;         f32x16 p0, p1;
; #pragma unroll
;         for (int r = 0; r < 16; ++r) { p0[r] = 0.f; p1[r] = 0.f; }
; #pragma unroll
;         for (int ds = 0; ds < 4; ++ds) {
;             const bf16x8 k0 = *(const LAS bf16x8*)(kb + ds * 32);
;             const bf16x8 k1 = *(const LAS bf16x8*)(kb + 32 * APITCH + ds * 32);
;             p0 = __builtin_amdgcn_mfma_f32_32x32x16_bf16(k0, qr[ds], p0, 0, 0, 0);
;             p1 = __builtin_amdgcn_mfma_f32_32x32x16_bf16(k1, qr[ds], p1, 0, 0, 0);
;         }
;         if (MODE == 0) {
;             const bool farl = (tok0 + 63 + 128 <= qtok0), farr = (tok0 - (qtok0 + 31) >= 128) && (tok0 + 64 <= LT);
;             if (farl || farr) { const float cb = farl ? mytab[0] : mytab[256];
; #pragma unroll
;                 for (int r = 0; r < 16; ++r) { p0[r] += cb; p1[r] += cb; } }
;             else {
; #pragma unroll
;                 for (int r = 0; r < 16; ++r) { const int tk0 = tok0 + crow(r, hi), tk1 = tk0 + 32;
;                     int i0 = tk0 - tq + 128; i0 = i0 < 0 ? 0 : (i0 > 256 ? 256 : i0); int i1 = tk1 - tq + 128; i1 = i1 < 0 ? 0 : (i1 > 256 ? 256 : i1);
;                     p0[r] = tk0 < LT ? p0[r] + mytab[i0] : NEGV; p1[r] = tk1 < LT ? p1[r] + mytab[i1] : NEGV; } }
;         } else if (MODE == 2) {
;           if (tok0 >= NMETA && tok0 + 64 <= LT) {
;             const LAS float* t2 = mytab2 + (tok0 - tq + 191 + 4 * hi);
; #pragma unroll
;             for (int r = 0; r < 16; ++r) { p0[r] += t2[(r & 3) + 8 * (r >> 2)]; p1[r] += t2[(r & 3) + 8 * (r >> 2) + 32]; }
;           } else
; #pragma unroll
;             for (int r = 0; r < 16; ++r) { const int tk0 = tok0 + crow(r, hi), tk1 = tk0 + 32; const int r0 = tk0 - tq, r1 = tk1 - tq;
;                 int i0 = r0 + 128; i0 = i0 < 0 ? 0 : (i0 > 256 ? 256 : i0); int i1 = r1 + 128; i1 = i1 < 0 ? 0 : (i1 > 256 ? 256 : i1);
.Lnat1R_loop:
	s_waitcnt lgkmcnt(0)
	s_barrier
	s_waitcnt vmcnt(7)
	ds_write_b128 v165, v[82:85]
	s_waitcnt vmcnt(6)
	ds_write_b128 v165, v[86:89] offset:9216
	s_waitcnt vmcnt(5)
	ds_write_b128 v165, v[90:93] offset:18432
	s_waitcnt vmcnt(4)
	ds_write_b128 v165, v[94:97] offset:27648
	s_waitcnt vmcnt(3)
	ds_write_b128 v165, v[98:101] offset:36864
	s_waitcnt vmcnt(2)
	ds_write_b128 v165, v[102:105] offset:46080
	s_waitcnt vmcnt(1)
	ds_write_b128 v165, v[106:109] offset:55296
	s_waitcnt vmcnt(0)
	ds_write_b128 v165, v[110:113] offset:64512
	s_waitcnt lgkmcnt(0)
	s_barrier
	v_mov_b32_e32 v117, s17
	v_cndmask_b32_e64 v117, v117, v116, s[44:45]
	v_lshl_add_u32 v184, v132, 2, v117
	ds_read_b128 v[118:121], v0
	ds_read_b128 v[128:131], v0 offset:4608
	ds_read_b128 v[168:171], v0 offset:32
	ds_read_b128 v[172:175], v0 offset:4640
	ds_read_b128 v[176:179], v0 offset:64
	ds_read_b128 v[180:183], v0 offset:4672
	ds_read2_b32 v[62:63], v184 offset0:24 offset1:25
	ds_read2_b32 v[64:65], v184 offset0:26 offset1:27
	ds_read2_b32 v[34:35], v184 offset0:32 offset1:33
	ds_read2_b32 v[36:37], v184 offset0:34 offset1:35
	ds_read2_b32 v[38:39], v184 offset0:40 offset1:41
	ds_read2_b32 v[40:41], v184 offset0:42 offset1:43
	ds_read2_b32 v[42:43], v184 offset0:48 offset1:49
	ds_read2_b32 v[44:45], v184 offset0:50 offset1:51
	ds_read2_b32 v[46:47], v184 offset0:56 offset1:57
	ds_read2_b32 v[48:49], v184 offset0:58 offset1:59
	s_cmpk_eq_i32 s12, 0x1c0
	s_cbranch_scc1 .Lnat1R_noload
	v_add_u32_e32 v206, s12, v115
	v_min_i32_e32 v206, 0x100f, v206
	v_mad_i64_i32 v[206:207], s[14:15], v206, s51, v[126:127]
	v_lshl_add_u64 v[208:209], v[206:207], 0, s[80:81]
	s_mov_b32 s1, s81
	s_mov_b32 s39, s81
	v_lshl_add_u64 v[210:211], v[206:207], 0, s[0:1]
	global_load_dwordx4 v[82:85], v[208:209], off
	global_load_dwordx4 v[86:89], v[210:211], off
	v_lshl_add_u64 v[208:209], v[206:207], 0, s[38:39]
	s_mov_b32 s43, s81
	s_mov_b32 s47, s81
	v_lshl_add_u64 v[210:211], v[206:207], 0, s[42:43]
	global_load_dwordx4 v[90:93], v[208:209], off
	global_load_dwordx4 v[94:97], v[210:211], off
	v_lshl_add_u64 v[208:209], v[206:207], 0, s[46:47]
	s_mov_b32 s49, s81
	s_mov_b32 s59, s81
	v_lshl_add_u64 v[210:211], v[206:207], 0, s[48:49]
	global_load_dwordx4 v[98:101], v[208:209], off
	global_load_dwordx4 v[102:105], v[210:211], off
	v_lshl_add_u64 v[208:209], v[206:207], 0, s[58:59]
	s_mov_b32 s61, s81
	v_lshl_add_u64 v[206:207], v[206:207], 0, s[60:61]
	global_load_dwordx4 v[106:109], v[208:209], off
	global_load_dwordx4 v[110:113], v[206:207], off
; template <int MODE> __device__ __forceinline__ void attn_unit(const AttnP& P, int u, LAS char* lds, bool fill) {
;     ...
;         for (int ds = 0; ds < 4; ++ds) {
;             const bf16x8 k0 = *(const LAS bf16x8*)(kb + ds * 32);
;             const bf16x8 k1 = *(const LAS bf16x8*)(kb + 32 * APITCH + ds * 32);
;             p0 = __builtin_amdgcn_mfma_f32_32x32x16_bf16(k0, qr[ds], p0, 0, 0, 0);
;             p1 = __builtin_amdgcn_mfma_f32_32x32x16_bf16(k1, qr[ds], p1, 0, 0, 0);
;         }
;         if (MODE == 0) {
;             const bool farl = (tok0 + 63 + 128 <= qtok0), farr = (tok0 - (qtok0 + 31) >= 128) && (tok0 + 64 <= LT);
;             if (farl || farr) { const float cb = farl ? mytab[0] : mytab[256];
; #pragma unroll
;                 for (int r = 0; r < 16; ++r) { p0[r] += cb; p1[r] += cb; } }
;             else {
; #pragma unroll
;                 for (int r = 0; r < 16; ++r) { const int tk0 = tok0 + crow(r, hi), tk1 = tk0 + 32;
;                     int i0 = tk0 - tq + 128; i0 = i0 < 0 ? 0 : (i0 > 256 ? 256 : i0); int i1 = tk1 - tq + 128; i1 = i1 < 0 ? 0 : (i1 > 256 ? 256 : i1);
;                     p0[r] = tk0 < LT ? p0[r] + mytab[i0] : NEGV; p1[r] = tk1 < LT ? p1[r] + mytab[i1] : NEGV; } }
;         } else if (MODE == 2) {
;           if (tok0 >= NMETA && tok0 + 64 <= LT) {
;             const LAS float* t2 = mytab2 + (tok0 - tq + 191 + 4 * hi);
; #pragma unroll
;             for (int r = 0; r < 16; ++r) { p0[r] += t2[(r & 3) + 8 * (r >> 2)]; p1[r] += t2[(r & 3) + 8 * (r >> 2) + 32]; }
;           } else
; #pragma unroll
;             for (int r = 0; r < 16; ++r) { const int tk0 = tok0 + crow(r, hi), tk1 = tk0 + 32; const int r0 = tk0 - tq, r1 = tk1 - tq;
;                 int i0 = r0 + 128; i0 = i0 < 0 ? 0 : (i0 > 256 ? 256 : i0); int i1 = r1 + 128; i1 = i1 < 0 ? 0 : (i1 > 256 ? 256 : i1);
;                 const bool v0 = (tk0 < NMETA || (r0 >= -128 && r0 <= 128)) && tk0 < LT, v1 = (tk1 < NMETA || (r1 >= -128 && r1 <= 128)) && tk1 < LT;
;                 p0[r] = v0 ? p0[r] + mytab[i0] : NEGV; p1[r] = v1 ? p1[r] + mytab[i1] : NEGV; }
;         } else {
;             if (t == 0) {
; #pragma unroll
;                 for (int r = 0; r < 16; ++r) { const int k0 = crow(r, hi); p0[r] = k0 < NMETA ? p0[r] : NEGV; p1[r] = NEGV; }
;             } else {
;                 const int roff = (rs_ + t - 1) - x2 + 7;
.Lnat1R_noload:
	s_waitcnt lgkmcnt(9)
	v_add_f32_e32 v62, v62, v157
	v_add_f32_e32 v63, v63, v159
	s_waitcnt lgkmcnt(8)
	v_add_f32_e32 v64, v64, v161
	v_add_f32_e32 v65, v65, v163
	s_waitcnt lgkmcnt(7)
	v_add_f32_e32 v34, v34, v134
	v_add_f32_e32 v35, v35, v136
	s_waitcnt lgkmcnt(6)
	v_add_f32_e32 v36, v36, v138
	v_add_f32_e32 v37, v37, v140
	s_waitcnt lgkmcnt(5)
	v_add_f32_e32 v38, v38, v142
	v_add_f32_e32 v39, v39, v144
	s_waitcnt lgkmcnt(4)
	v_add_f32_e32 v40, v40, v146
	v_add_f32_e32 v41, v41, v148
	s_waitcnt lgkmcnt(3)
	v_add_f32_e32 v42, v42, v150
	v_add_f32_e32 v43, v43, v152
	s_waitcnt lgkmcnt(2)
	v_add_f32_e32 v44, v44, v154
	v_add_f32_e32 v45, v45, v156
	s_waitcnt lgkmcnt(1)
	v_add_f32_e32 v46, v46, v158
	v_add_f32_e32 v47, v47, v160
	s_waitcnt lgkmcnt(0)
	v_add_f32_e32 v48, v48, v162
	v_add_f32_e32 v49, v49, v164
	v_mfma_f32_32x32x16_bf16 v[50:65], v[118:121], v[66:69], v[50:65]
	ds_read_b128 v[118:121], v0 offset:96
	v_mfma_f32_32x32x16_bf16 v[34:49], v[128:131], v[66:69], v[34:49]
	ds_read_b128 v[128:131], v0 offset:4704
	v_mfma_f32_32x32x16_bf16 v[50:65], v[168:171], v[70:73], v[50:65]
	ds_read_b64_tr_b16 v[168:169], v166 offset:11520
	ds_read_b64_tr_b16 v[170:171], v166 offset:12672
	v_mfma_f32_32x32x16_bf16 v[34:49], v[172:175], v[70:73], v[34:49]
	ds_read_b64_tr_b16 v[172:173], v166 offset:11584
	ds_read_b64_tr_b16 v[174:175], v166 offset:12736
	v_mfma_f32_32x32x16_bf16 v[50:65], v[176:179], v[74:77], v[50:65]
	ds_read_b64_tr_b16 v[176:177], v166 offset:13824
	ds_read_b64_tr_b16 v[178:179], v166 offset:14976
	v_mfma_f32_32x32x16_bf16 v[34:49], v[180:183], v[74:77], v[34:49]
	ds_read_b64_tr_b16 v[180:181], v166 offset:13888
	ds_read_b64_tr_b16 v[182:183], v166 offset:15040
	s_waitcnt lgkmcnt(9)
	v_mfma_f32_32x32x16_bf16 v[50:65], v[118:121], v[78:81], v[50:65]
	s_waitcnt lgkmcnt(8)
	v_mfma_f32_32x32x16_bf16 v[34:49], v[128:131], v[78:81], v[34:49]
	ds_read_b64_tr_b16 v[118:119], v166 offset:16128
	ds_read_b64_tr_b16 v[120:121], v166 offset:17280
	ds_read_b64_tr_b16 v[128:129], v166 offset:16192
	ds_read_b64_tr_b16 v[130:131], v166 offset:17344
	s_nop 7
	v_max3_f32 v117, v62, v63, v64
	v_max3_f32 v184, v40, v41, v42
	v_max3_f32 v117, v117, v65, v34
	v_max3_f32 v184, v184, v43, v44
	v_max3_f32 v117, v117, v35, v36
	v_max3_f32 v184, v184, v45, v46
	v_max3_f32 v117, v117, v37, v38
	v_max3_f32 v184, v184, v47, v48
	v_max3_f32 v117, v117, v39, v49
	v_max_f32_e32 v117, v117, v184
	v_mov_b32_e32 v184, v117
	s_nop 1
	v_permlane32_swap_b32_e32 v117, v184
	v_max_f32_e32 v117, v117, v184
	v_cmp_lt_f32_e32 vcc, 0x41000000, v117
	s_cbranch_vccz .Lnat1R_noresc
	v_max_f32_e32 v117, 0, v117
	v_exp_f32_e64 v184, -v117
	v_add_f32_e32 v167, v167, v117
	v_sub_f32_e32 v157, v157, v117
	v_sub_f32_e32 v159, v159, v117
	v_sub_f32_e32 v161, v161, v117
	v_sub_f32_e32 v163, v163, v117
	v_sub_f32_e32 v134, v134, v117
	v_sub_f32_e32 v136, v136, v117
	v_sub_f32_e32 v138, v138, v117
	v_sub_f32_e32 v140, v140, v117
	v_sub_f32_e32 v142, v142, v117
	v_sub_f32_e32 v144, v144, v117
	v_sub_f32_e32 v146, v146, v117
	v_sub_f32_e32 v148, v148, v117
	v_sub_f32_e32 v150, v150, v117
	v_sub_f32_e32 v152, v152, v117
	v_sub_f32_e32 v154, v154, v117
	v_sub_f32_e32 v156, v156, v117
	v_sub_f32_e32 v158, v158, v117
	v_sub_f32_e32 v160, v160, v117
	v_sub_f32_e32 v162, v162, v117
	v_sub_f32_e32 v164, v164, v117
	v_sub_f32_e32 v62, v62, v117
	v_sub_f32_e32 v63, v63, v117
	v_sub_f32_e32 v64, v64, v117
	v_sub_f32_e32 v65, v65, v117
	v_sub_f32_e32 v34, v34, v117
	v_sub_f32_e32 v35, v35, v117
	v_sub_f32_e32 v36, v36, v117
	v_sub_f32_e32 v37, v37, v117
	v_sub_f32_e32 v38, v38, v117
	v_sub_f32_e32 v39, v39, v117
	v_sub_f32_e32 v40, v40, v117
	v_sub_f32_e32 v41, v41, v117
	v_sub_f32_e32 v42, v42, v117
	v_sub_f32_e32 v43, v43, v117
	v_sub_f32_e32 v44, v44, v117
	v_sub_f32_e32 v45, v45, v117
	v_sub_f32_e32 v46, v46, v117
	v_sub_f32_e32 v47, v47, v117
	v_sub_f32_e32 v48, v48, v117
	v_sub_f32_e32 v49, v49, v117
	v_mul_f32_e32 v2, v2, v184
	v_mul_f32_e32 v3, v3, v184
	v_mul_f32_e32 v4, v4, v184
	v_mul_f32_e32 v5, v5, v184
	v_mul_f32_e32 v6, v6, v184
	v_mul_f32_e32 v7, v7, v184
	v_mul_f32_e32 v8, v8, v184
	v_mul_f32_e32 v9, v9, v184
	v_mul_f32_e32 v10, v10, v184
	v_mul_f32_e32 v11, v11, v184
	v_mul_f32_e32 v12, v12, v184
	v_mul_f32_e32 v13, v13, v184
	v_mul_f32_e32 v14, v14, v184
	v_mul_f32_e32 v15, v15, v184
	v_mul_f32_e32 v16, v16, v184
	v_mul_f32_e32 v17, v17, v184
	v_mul_f32_e32 v18, v18, v184
	v_mul_f32_e32 v19, v19, v184
	v_mul_f32_e32 v20, v20, v184
	v_mul_f32_e32 v21, v21, v184
	v_mul_f32_e32 v22, v22, v184
	v_mul_f32_e32 v23, v23, v184
	v_mul_f32_e32 v24, v24, v184
	v_mul_f32_e32 v25, v25, v184
	v_mul_f32_e32 v26, v26, v184
	v_mul_f32_e32 v27, v27, v184
	v_mul_f32_e32 v28, v28, v184
	v_mul_f32_e32 v29, v29, v184
	v_mul_f32_e32 v30, v30, v184
	v_mul_f32_e32 v31, v31, v184
	v_mul_f32_e32 v32, v32, v184
	v_mul_f32_e32 v33, v33, v184
	v_mul_f32_e32 v114, v114, v184
	s_nop 1

; #define LAS __attribute__((address_space(3)))
; __device__ __forceinline__ int crow(int r, int hi) { return (r & 3) + 8 * (r >> 2) + 4 * hi; }
; #define ISSUE(t) do { int tok_ = TILE_TOK0(t) + lrow; tok_ = tok_ > LT - 1 ? LT - 1 : tok_; const bf16_t* src_ = pb + (size_t)tok_ * INC; \
;         _Pragma("unroll") for (int s = 0; s < NS; ++s) pre[s] = *(const u32x4*)(src_ + STREAM_COL(s)); } while (0)
; template <int MODE> __device__ __forceinline__ void attn_unit(const AttnP& P, int u, LAS char* lds, bool fill) {
;     ...
;     for (int t = 0; t < nt; ++t) {
;         __syncthreads();
; #pragma unroll
;         for (int s = 0; s < NS; ++s) *(LAS u32x4*)(lds + s * ASLOT + lrow * APITCH + lch * 16) = pre[s];
;         __syncthreads();
;         if (t + 1 < nt) ISSUE(t + 1);
;         const int tok0 = TILE_TOK0(t);
;         f32x16 p0, p1;
; #pragma unroll
;         for (int r = 0; r < 16; ++r) { p0[r] = 0.f; p1[r] = 0.f; }
; #pragma unroll
;         for (int ds = 0; ds < 4; ++ds) {
;             const bf16x8 k0 = *(const LAS bf16x8*)(kb + ds * 32);
;             const bf16x8 k1 = *(const LAS bf16x8*)(kb + 32 * APITCH + ds * 32);
;             p0 = __builtin_amdgcn_mfma_f32_32x32x16_bf16(k0, qr[ds], p0, 0, 0, 0);
;             p1 = __builtin_amdgcn_mfma_f32_32x32x16_bf16(k1, qr[ds], p1, 0, 0, 0);
;         }
;         if (MODE == 0) {
;             const bool farl = (tok0 + 63 + 128 <= qtok0), farr = (tok0 - (qtok0 + 31) >= 128) && (tok0 + 64 <= LT);
;             if (farl || farr) { const float cb = farl ? mytab[0] : mytab[256];
; #pragma unroll
;                 for (int r = 0; r < 16; ++r) { p0[r] += cb; p1[r] += cb; } }
;             else {
; #pragma unroll
;                 for (int r = 0; r < 16; ++r) { const int tk0 = tok0 + crow(r, hi), tk1 = tk0 + 32;
;                     int i0 = tk0 - tq + 128; i0 = i0 < 0 ? 0 : (i0 > 256 ? 256 : i0); int i1 = tk1 - tq + 128; i1 = i1 < 0 ? 0 : (i1 > 256 ? 256 : i1);
;                     p0[r] = tk0 < LT ? p0[r] + mytab[i0] : NEGV; p1[r] = tk1 < LT ? p1[r] + mytab[i1] : NEGV; } }
;         } else if (MODE == 2) {
;           if (tok0 >= NMETA && tok0 + 64 <= LT) {
;             const LAS float* t2 = mytab2 + (tok0 - tq + 191 + 4 * hi);
; #pragma unroll
;             for (int r = 0; r < 16; ++r) { p0[r] += t2[(r & 3) + 8 * (r >> 2)]; p1[r] += t2[(r & 3) + 8 * (r >> 2) + 32]; }
.LBB0_1266:
	s_add_i32 s39, s39, 1
	s_waitcnt lgkmcnt(0)
	s_barrier
	s_waitcnt vmcnt(1)
	ds_write_b128 v0, v[118:121]
	s_waitcnt vmcnt(0)
	ds_write_b128 v0, v[114:117] offset:9216
	s_waitcnt lgkmcnt(0)
	s_barrier
	s_add_i32 s15, s38, s35
	s_add_i32 s16, s15, 48
	s_cmpk_lt_u32 s16, 0xfc1
	s_cbranch_scc0 .Lgqa2_slowpre
	ds_read_b128 v[66:69], v127
	ds_read_b128 v[70:73], v127 offset:4608
	ds_read_b128 v[74:77], v127 offset:32
	ds_read_b128 v[78:81], v127 offset:4640
	ds_read_b128 v[82:85], v127 offset:64
	ds_read_b128 v[86:89], v127 offset:4672
	ds_read_b128 v[90:93], v127 offset:96
	ds_read_b128 v[94:97], v127 offset:4704
	ds_read2_b32 v[34:35], v131 offset0:0 offset1:1
	ds_read2_b32 v[36:37], v131 offset0:2 offset1:3
	ds_read2_b32 v[38:39], v131 offset0:8 offset1:9
	ds_read2_b32 v[40:41], v131 offset0:10 offset1:11
	ds_read2_b32 v[42:43], v131 offset0:16 offset1:17
	ds_read2_b32 v[44:45], v131 offset0:18 offset1:19
	ds_read2_b32 v[46:47], v131 offset0:24 offset1:25
	ds_read2_b32 v[48:49], v131 offset0:26 offset1:27
	ds_read2_b32 v[50:51], v131 offset0:32 offset1:33
	ds_read2_b32 v[52:53], v131 offset0:34 offset1:35
	ds_read2_b32 v[54:55], v131 offset0:40 offset1:41
	ds_read2_b32 v[56:57], v131 offset0:42 offset1:43
	ds_read2_b32 v[58:59], v131 offset0:48 offset1:49
	ds_read2_b32 v[60:61], v131 offset0:50 offset1:51
	ds_read2_b32 v[62:63], v131 offset0:56 offset1:57
	ds_read2_b32 v[64:65], v131 offset0:58 offset1:59
	s_cmp_ge_i32 s39, s31
	s_cbranch_scc1 .Lgqa2_noload
	s_add_i32 s15, s35, 0x80
	s_add_i32 s16, s14, s35
	s_and_b64 s[0:1], s[46:47], exec
	s_cselect_b32 s0, s16, s15
	v_add_u32_e32 v206, s0, v126
	v_min_i32_e32 v206, 0x100f, v206
	v_mad_i64_i32 v[206:207], s[0:1], v206, s51, v[122:123]
	v_lshl_add_u64 v[208:209], s[48:49], 1, v[206:207]
	v_lshl_add_u64 v[206:207], s[58:59], 1, v[206:207]
	global_load_dwordx4 v[118:121], v[208:209], off
	global_load_dwordx4 v[114:117], v[206:207], off

; #define LAS __attribute__((address_space(3)))
; template <int MODE> __device__ __forceinline__ void attn_unit(const AttnP& P, int u, LAS char* lds, bool fill) {
;     ...
;         if (t + 1 < nt) ISSUE(t + 1);
;         const int tok0 = TILE_TOK0(t);
;         f32x16 p0, p1;
; #pragma unroll
;         for (int r = 0; r < 16; ++r) { p0[r] = 0.f; p1[r] = 0.f; }
; #pragma unroll
;         for (int ds = 0; ds < 4; ++ds) {
;             const bf16x8 k0 = *(const LAS bf16x8*)(kb + ds * 32);
;             const bf16x8 k1 = *(const LAS bf16x8*)(kb + 32 * APITCH + ds * 32);
;             p0 = __builtin_amdgcn_mfma_f32_32x32x16_bf16(k0, qr[ds], p0, 0, 0, 0);
;             p1 = __builtin_amdgcn_mfma_f32_32x32x16_bf16(k1, qr[ds], p1, 0, 0, 0);
;         }
;         if (MODE == 0) {
;             const bool farl = (tok0 + 63 + 128 <= qtok0), farr = (tok0 - (qtok0 + 31) >= 128) && (tok0 + 64 <= LT);
;             if (farl || farr) { const float cb = farl ? mytab[0] : mytab[256];
; #pragma unroll
;                 for (int r = 0; r < 16; ++r) { p0[r] += cb; p1[r] += cb; } }
;             else {
; #pragma unroll
;                 for (int r = 0; r < 16; ++r) { const int tk0 = tok0 + crow(r, hi), tk1 = tk0 + 32;
;                     int i0 = tk0 - tq + 128; i0 = i0 < 0 ? 0 : (i0 > 256 ? 256 : i0); int i1 = tk1 - tq + 128; i1 = i1 < 0 ? 0 : (i1 > 256 ? 256 : i1);
;                     p0[r] = tk0 < LT ? p0[r] + mytab[i0] : NEGV; p1[r] = tk1 < LT ? p1[r] + mytab[i1] : NEGV; } }
;         } else if (MODE == 2) {
;           if (tok0 >= NMETA && tok0 + 64 <= LT) {
;             const LAS float* t2 = mytab2 + (tok0 - tq + 191 + 4 * hi);
; #pragma unroll
;             for (int r = 0; r < 16; ++r) { p0[r] += t2[(r & 3) + 8 * (r >> 2)]; p1[r] += t2[(r & 3) + 8 * (r >> 2) + 32]; }
;           } else
; #pragma unroll
;             for (int r = 0; r < 16; ++r) { const int tk0 = tok0 + crow(r, hi), tk1 = tk0 + 32; const int r0 = tk0 - tq, r1 = tk1 - tq;
;                 int i0 = r0 + 128; i0 = i0 < 0 ? 0 : (i0 > 256 ? 256 : i0); int i1 = r1 + 128; i1 = i1 < 0 ? 0 : (i1 > 256 ? 256 : i1);
;                 const bool v0 = (tk0 < NMETA || (r0 >= -128 && r0 <= 128)) && tk0 < LT, v1 = (tk1 < NMETA || (r1 >= -128 && r1 <= 128)) && tk1 < LT;
;                 p0[r] = v0 ? p0[r] + mytab[i0] : NEGV; p1[r] = v1 ? p1[r] + mytab[i1] : NEGV; }
.Lgqa2_slowpre:
	s_cmp_ge_i32 s39, s31
	s_cbranch_scc1 .Lgqa2_noload_s
	s_add_i32 s15, s35, 0x80
	s_add_i32 s16, s14, s35
	s_and_b64 s[0:1], s[46:47], exec
	s_cselect_b32 s0, s16, s15
	v_add_u32_e32 v34, s0, v126
	v_min_i32_e32 v34, 0x100f, v34
	v_mad_i64_i32 v[34:35], s[0:1], v34, s51, v[122:123]
	v_lshl_add_u64 v[36:37], s[48:49], 1, v[34:35]
	v_lshl_add_u64 v[34:35], s[58:59], 1, v[34:35]
	global_load_dwordx4 v[118:121], v[36:37], off
	global_load_dwordx4 v[114:117], v[34:35], off
.Lgqa2_noload_s:
	s_add_i32 s15, s38, s35
	s_add_i32 s16, s15, 48
.Lgqa2_slow:
	ds_read_b128 v[34:37], v127 offset:4608
	ds_read_b128 v[38:41], v127
	ds_read_b128 v[42:45], v127 offset:32
	s_add_i32 s15, s38, s35
	s_add_i32 s16, s15, 48
	s_waitcnt lgkmcnt(2)
	v_mfma_f32_32x32x16_bf16 v[66:81], v[34:37], v[98:101], 0
	ds_read_b128 v[34:37], v127 offset:4640
	s_mov_b64 s[0:1], -1
	s_cmpk_lt_u32 s16, 0xfc1
	s_waitcnt lgkmcnt(2)
	v_mfma_f32_32x32x16_bf16 v[82:97], v[38:41], v[98:101], 0
	s_waitcnt lgkmcnt(1)
	v_mfma_f32_32x32x16_bf16 v[82:97], v[42:45], v[102:105], v[82:97]
	s_waitcnt lgkmcnt(0)
	v_mfma_f32_32x32x16_bf16 v[66:81], v[34:37], v[102:105], v[66:81]
	ds_read_b128 v[34:37], v127 offset:64
	ds_read_b128 v[38:41], v127 offset:4672
	s_waitcnt lgkmcnt(1)
	v_mfma_f32_32x32x16_bf16 v[82:97], v[34:37], v[106:109], v[82:97]
	s_waitcnt lgkmcnt(0)
	v_mfma_f32_32x32x16_bf16 v[66:81], v[38:41], v[106:109], v[66:81]
	ds_read_b128 v[34:37], v127 offset:96
	ds_read_b128 v[38:41], v127 offset:4704
	s_waitcnt lgkmcnt(1)
	v_mfma_f32_32x32x16_bf16 v[82:97], v[34:37], v[110:113], v[82:97]
	s_waitcnt lgkmcnt(0)
	v_mfma_f32_32x32x16_bf16 v[66:81], v[38:41], v[110:113], v[66:81]
	v_add_u32_e32 v49, s35, v132
	v_add_u32_e32 v134, s35, v133
	v_add_u32_e32 v35, 64, v49
	v_add_u32_e32 v34, 0xc0, v134
	v_cmp_gt_i32_e32 vcc, 16, v35
	v_cmp_gt_u32_e64 s[44:45], s6, v34
	s_or_b64 s[0:1], vcc, s[44:45]
	v_cmp_gt_i32_e32 vcc, s37, v35
	s_and_b64 s[28:29], vcc, s[0:1]
	v_mov_b32_e32 v50, 0xf149f2ca
	v_mov_b32_e32 v34, 0xf149f2ca
	s_and_saveexec_b64 s[0:1], s[28:29]
	s_cbranch_execz .LBB0_1271
	v_add_u32_e32 v34, 64, v134
	v_med3_i32 v34, v34, s87, v240
	v_lshl_add_u32 v34, v34, 2, s34
	ds_read_b32 v34, v34 offset:512
	s_waitcnt lgkmcnt(0)
	v_add_f32_e32 v34, v82, v34

; #define LAS __attribute__((address_space(3)))
; template <int MODE> __device__ __forceinline__ void attn_unit(const AttnP& P, int u, LAS char* lds, bool fill) {
;     ...
;     for (int t = 0; t < nt; ++t) {
;         __syncthreads();
; #pragma unroll
;         for (int s = 0; s < NS; ++s) *(LAS u32x4*)(lds + s * ASLOT + lrow * APITCH + lch * 16) = pre[s];
;         __syncthreads();
;         if (t + 1 < nt) ISSUE(t + 1);
;         const int tok0 = TILE_TOK0(t);
;         f32x16 p0, p1;
; #pragma unroll
;         for (int r = 0; r < 16; ++r) { p0[r] = 0.f; p1[r] = 0.f; }
; #pragma unroll
;         for (int ds = 0; ds < 4; ++ds) {
;             const bf16x8 k0 = *(const LAS bf16x8*)(kb + ds * 32);
;             const bf16x8 k1 = *(const LAS bf16x8*)(kb + 32 * APITCH + ds * 32);
;             p0 = __builtin_amdgcn_mfma_f32_32x32x16_bf16(k0, qr[ds], p0, 0, 0, 0);
;             p1 = __builtin_amdgcn_mfma_f32_32x32x16_bf16(k1, qr[ds], p1, 0, 0, 0);
;         }
;         if (MODE == 0) {
;             const bool farl = (tok0 + 63 + 128 <= qtok0), farr = (tok0 - (qtok0 + 31) >= 128) && (tok0 + 64 <= LT);
;             if (farl || farr) { const float cb = farl ? mytab[0] : mytab[256];
; #pragma unroll
;                 for (int r = 0; r < 16; ++r) { p0[r] += cb; p1[r] += cb; } }
;             else {
; #pragma unroll
;                 for (int r = 0; r < 16; ++r) { const int tk0 = tok0 + crow(r, hi), tk1 = tk0 + 32;
;                     int i0 = tk0 - tq + 128; i0 = i0 < 0 ? 0 : (i0 > 256 ? 256 : i0); int i1 = tk1 - tq + 128; i1 = i1 < 0 ? 0 : (i1 > 256 ? 256 : i1);
;                     p0[r] = tk0 < LT ? p0[r] + mytab[i0] : NEGV; p1[r] = tk1 < LT ? p1[r] + mytab[i1] : NEGV; } }
;         } else if (MODE == 2) {
;           if (tok0 >= NMETA && tok0 + 64 <= LT) {
;             const LAS float* t2 = mytab2 + (tok0 - tq + 191 + 4 * hi);
; #pragma unroll
;             for (int r = 0; r < 16; ++r) { p0[r] += t2[(r & 3) + 8 * (r >> 2)]; p1[r] += t2[(r & 3) + 8 * (r >> 2) + 32]; }
;           } else
; #pragma unroll
;             for (int r = 0; r < 16; ++r) { const int tk0 = tok0 + crow(r, hi), tk1 = tk0 + 32; const int r0 = tk0 - tq, r1 = tk1 - tq;
;                 int i0 = r0 + 128; i0 = i0 < 0 ? 0 : (i0 > 256 ? 256 : i0); int i1 = r1 + 128; i1 = i1 < 0 ? 0 : (i1 > 256 ? 256 : i1);
.Lnat2L_loop:
	s_waitcnt lgkmcnt(0)
	s_barrier
	s_waitcnt vmcnt(7)
	ds_write_b128 v165, v[82:85]
	s_waitcnt vmcnt(6)
	ds_write_b128 v165, v[86:89] offset:9216
	s_waitcnt vmcnt(5)
	ds_write_b128 v165, v[90:93] offset:18432
	s_waitcnt vmcnt(4)
	ds_write_b128 v165, v[94:97] offset:27648
	s_waitcnt vmcnt(3)
	ds_write_b128 v165, v[98:101] offset:36864
	s_waitcnt vmcnt(2)
	ds_write_b128 v165, v[102:105] offset:46080
	s_waitcnt vmcnt(1)
	ds_write_b128 v165, v[106:109] offset:55296
	s_waitcnt vmcnt(0)
	ds_write_b128 v165, v[110:113] offset:64512
	s_waitcnt lgkmcnt(0)
	s_barrier
	v_mov_b32_e32 v117, s17
	v_cndmask_b32_e64 v117, v117, v116, s[44:45]
	v_lshl_add_u32 v184, v132, 2, v117
	ds_read_b128 v[118:121], v0
	ds_read_b128 v[128:131], v0 offset:4608
	ds_read_b128 v[168:171], v0 offset:32
	ds_read_b128 v[172:175], v0 offset:4640
	ds_read_b128 v[176:179], v0 offset:64
	ds_read_b128 v[180:183], v0 offset:4672
	ds_read2_b32 v[50:51], v184 offset0:0 offset1:1
	ds_read2_b32 v[52:53], v184 offset0:2 offset1:3
	ds_read2_b32 v[54:55], v184 offset0:8 offset1:9
	ds_read2_b32 v[56:57], v184 offset0:10 offset1:11
	ds_read2_b32 v[58:59], v184 offset0:16 offset1:17
	ds_read2_b32 v[60:61], v184 offset0:18 offset1:19
	ds_read2_b32 v[62:63], v184 offset0:24 offset1:25
	ds_read2_b32 v[64:65], v184 offset0:26 offset1:27
	ds_read2_b32 v[34:35], v184 offset0:32 offset1:33
	ds_read2_b32 v[36:37], v184 offset0:34 offset1:35
	s_cmpk_eq_i32 s13, 0x1c0
	s_cbranch_scc1 .Lnat2L_noload
	v_add_u32_e32 v206, s13, v115
	v_min_i32_e32 v206, 0x100f, v206
	v_mad_i64_i32 v[206:207], s[14:15], v206, s51, v[126:127]
	v_lshl_add_u64 v[208:209], s[42:43], 1, v[206:207]
	v_lshl_add_u64 v[210:211], s[58:59], 1, v[206:207]
	global_load_dwordx4 v[82:85], v[208:209], off
	global_load_dwordx4 v[86:89], v[210:211], off
	v_lshl_add_u64 v[208:209], s[60:61], 1, v[206:207]
	v_lshl_add_u64 v[210:211], s[62:63], 1, v[206:207]
	global_load_dwordx4 v[90:93], v[208:209], off
	global_load_dwordx4 v[94:97], v[210:211], off
	v_lshl_add_u64 v[208:209], s[64:65], 1, v[206:207]
	v_lshl_add_u64 v[210:211], s[66:67], 1, v[206:207]
	global_load_dwordx4 v[98:101], v[208:209], off
	global_load_dwordx4 v[102:105], v[210:211], off
	v_lshl_add_u64 v[208:209], s[38:39], 1, v[206:207]
	v_lshl_add_u64 v[206:207], s[0:1], 1, v[206:207]
	global_load_dwordx4 v[106:109], v[208:209], off
	global_load_dwordx4 v[110:113], v[206:207], off

; #define LAS __attribute__((address_space(3)))
; template <int MODE> __device__ __forceinline__ void attn_unit(const AttnP& P, int u, LAS char* lds, bool fill) {
;     ...
;     for (int t = 0; t < nt; ++t) {
;         __syncthreads();
; #pragma unroll
;         for (int s = 0; s < NS; ++s) *(LAS u32x4*)(lds + s * ASLOT + lrow * APITCH + lch * 16) = pre[s];
;         __syncthreads();
;         if (t + 1 < nt) ISSUE(t + 1);
;         const int tok0 = TILE_TOK0(t);
;         f32x16 p0, p1;
; #pragma unroll
;         for (int r = 0; r < 16; ++r) { p0[r] = 0.f; p1[r] = 0.f; }
; #pragma unroll
;         for (int ds = 0; ds < 4; ++ds) {
;             const bf16x8 k0 = *(const LAS bf16x8*)(kb + ds * 32);
;             const bf16x8 k1 = *(const LAS bf16x8*)(kb + 32 * APITCH + ds * 32);
;             p0 = __builtin_amdgcn_mfma_f32_32x32x16_bf16(k0, qr[ds], p0, 0, 0, 0);
;             p1 = __builtin_amdgcn_mfma_f32_32x32x16_bf16(k1, qr[ds], p1, 0, 0, 0);
;         }
;         if (MODE == 0) {
;             const bool farl = (tok0 + 63 + 128 <= qtok0), farr = (tok0 - (qtok0 + 31) >= 128) && (tok0 + 64 <= LT);
;             if (farl || farr) { const float cb = farl ? mytab[0] : mytab[256];
; #pragma unroll
;                 for (int r = 0; r < 16; ++r) { p0[r] += cb; p1[r] += cb; } }
;             else {
; #pragma unroll
;                 for (int r = 0; r < 16; ++r) { const int tk0 = tok0 + crow(r, hi), tk1 = tk0 + 32;
;                     int i0 = tk0 - tq + 128; i0 = i0 < 0 ? 0 : (i0 > 256 ? 256 : i0); int i1 = tk1 - tq + 128; i1 = i1 < 0 ? 0 : (i1 > 256 ? 256 : i1);
;                     p0[r] = tk0 < LT ? p0[r] + mytab[i0] : NEGV; p1[r] = tk1 < LT ? p1[r] + mytab[i1] : NEGV; } }
;         } else if (MODE == 2) {
;           if (tok0 >= NMETA && tok0 + 64 <= LT) {
;             const LAS float* t2 = mytab2 + (tok0 - tq + 191 + 4 * hi);
; #pragma unroll
;             for (int r = 0; r < 16; ++r) { p0[r] += t2[(r & 3) + 8 * (r >> 2)]; p1[r] += t2[(r & 3) + 8 * (r >> 2) + 32]; }
;           } else
; #pragma unroll
;             for (int r = 0; r < 16; ++r) { const int tk0 = tok0 + crow(r, hi), tk1 = tk0 + 32; const int r0 = tk0 - tq, r1 = tk1 - tq;
;                 int i0 = r0 + 128; i0 = i0 < 0 ? 0 : (i0 > 256 ? 256 : i0); int i1 = r1 + 128; i1 = i1 < 0 ? 0 : (i1 > 256 ? 256 : i1);
.Lnat2R_loop:
	s_waitcnt lgkmcnt(0)
	s_barrier
	s_waitcnt vmcnt(7)
	ds_write_b128 v165, v[82:85]
	s_waitcnt vmcnt(6)
	ds_write_b128 v165, v[86:89] offset:9216
	s_waitcnt vmcnt(5)
	ds_write_b128 v165, v[90:93] offset:18432
	s_waitcnt vmcnt(4)
	ds_write_b128 v165, v[94:97] offset:27648
	s_waitcnt vmcnt(3)
	ds_write_b128 v165, v[98:101] offset:36864
	s_waitcnt vmcnt(2)
	ds_write_b128 v165, v[102:105] offset:46080
	s_waitcnt vmcnt(1)
	ds_write_b128 v165, v[106:109] offset:55296
	s_waitcnt vmcnt(0)
	ds_write_b128 v165, v[110:113] offset:64512
	s_waitcnt lgkmcnt(0)
	s_barrier
	v_mov_b32_e32 v117, s17
	v_cndmask_b32_e64 v117, v117, v116, s[44:45]
	v_lshl_add_u32 v184, v132, 2, v117
	ds_read_b128 v[118:121], v0
	ds_read_b128 v[128:131], v0 offset:4608
	ds_read_b128 v[168:171], v0 offset:32
	ds_read_b128 v[172:175], v0 offset:4640
	ds_read_b128 v[176:179], v0 offset:64
	ds_read_b128 v[180:183], v0 offset:4672
	ds_read2_b32 v[62:63], v184 offset0:24 offset1:25
	ds_read2_b32 v[64:65], v184 offset0:26 offset1:27
	ds_read2_b32 v[34:35], v184 offset0:32 offset1:33
	ds_read2_b32 v[36:37], v184 offset0:34 offset1:35
	ds_read2_b32 v[38:39], v184 offset0:40 offset1:41
	ds_read2_b32 v[40:41], v184 offset0:42 offset1:43
	ds_read2_b32 v[42:43], v184 offset0:48 offset1:49
	ds_read2_b32 v[44:45], v184 offset0:50 offset1:51
	ds_read2_b32 v[46:47], v184 offset0:56 offset1:57
	ds_read2_b32 v[48:49], v184 offset0:58 offset1:59
	s_cmpk_eq_i32 s13, 0x1c0
	s_cbranch_scc1 .Lnat2R_noload
	v_add_u32_e32 v206, s13, v115
	v_min_i32_e32 v206, 0x100f, v206
	v_mad_i64_i32 v[206:207], s[14:15], v206, s51, v[126:127]
	v_lshl_add_u64 v[208:209], s[42:43], 1, v[206:207]
	v_lshl_add_u64 v[210:211], s[58:59], 1, v[206:207]
	global_load_dwordx4 v[82:85], v[208:209], off
	global_load_dwordx4 v[86:89], v[210:211], off
	v_lshl_add_u64 v[208:209], s[60:61], 1, v[206:207]
	v_lshl_add_u64 v[210:211], s[62:63], 1, v[206:207]
	global_load_dwordx4 v[90:93], v[208:209], off
	global_load_dwordx4 v[94:97], v[210:211], off
	v_lshl_add_u64 v[208:209], s[64:65], 1, v[206:207]
	v_lshl_add_u64 v[210:211], s[66:67], 1, v[206:207]
	global_load_dwordx4 v[98:101], v[208:209], off
	global_load_dwordx4 v[102:105], v[210:211], off
	v_lshl_add_u64 v[208:209], s[38:39], 1, v[206:207]
	v_lshl_add_u64 v[206:207], s[0:1], 1, v[206:207]
	global_load_dwordx4 v[106:109], v[208:209], off
	global_load_dwordx4 v[110:113], v[206:207], off
